# v16_nodrain
# baseline (speedup 1.0000x reference)
; DEVI float bfs(short h) { return __uint_as_float(((unsigned)(u16)h) << 16); }
; DEVI float silu_f(float x) { return x * __builtin_amdgcn_rcpf(1.f + __expf(-x)); }
; DEVI float xq_sum(float v) { v += __shfl_xor(v, 16); v += __shfl_xor(v, 32); return v; }
; DEVI void moba_item(const Params& p, int l, int item) {
;     ...
;   lsum = xq_sum(lsum);
;   const float inv = __builtin_amdgcn_rcpf(lsum);
;   const long qtok = t0 + w * 16 + fr;
;   bf16x4 gtv[8];
; #pragma unroll
;   for (int ct = 0; ct < 8; ++ct) gtv[ct] = *(const bf16x4*)(proj + qtok * NP + C_CGATE + h * 128 + ct * 16 + fq * 4);
; #pragma unroll
;   for (int ct = 0; ct < 8; ++ct) {
;     int dv = ct * 16 + fq * 4;
;     const bf16x4 gt = gtv[ct];
;     *(bf16x4*)(p.ys + (long)2 * T_ * 1024 + qtok * 1024 + h * 128 + dv) =
;         pack4(oacc[ct][0] * inv * silu_f(bfs(gt[0])), oacc[ct][1] * inv * silu_f(bfs(gt[1])),
;               oacc[ct][2] * inv * silu_f(bfs(gt[2])), oacc[ct][3] * inv * silu_f(bfs(gt[3])));
;   }
.LBB0_493:
	v_cmp_lt_i32_e32 vcc, v232, v252
	v_or_b32_e32 v210, s27, v156
	s_waitcnt vmcnt(5)
	v_lshlrev_b32_e32 v10, 1, v158
	v_cndmask_b32_e32 v0, v235, v232, vcc
	v_lshlrev_b32_e32 v0, 2, v0
	ds_bpermute_b32 v0, v0, v144
	v_cmp_lt_i32_e32 vcc, v226, v252
	v_mov_b32_e32 v11, v211
	s_waitcnt lgkmcnt(0)
	v_add_f32_e32 v0, v144, v0
	v_cndmask_b32_e32 v1, v235, v226, vcc
	v_lshlrev_b32_e32 v1, 2, v1
	ds_bpermute_b32 v1, v1, v0
	s_waitcnt vmcnt(2) lgkmcnt(0)
	v_add_f32_e32 v20, v0, v1
	v_mov_b64_e32 v[0:1], s[92:93]
	v_mad_u64_u32 v[0:1], s[2:3], v210, s97, v[0:1]
	v_lshl_add_u64 v[0:1], v[0:1], 0, s[98:99]
	v_lshl_add_u64 v[0:1], v[0:1], 0, v[10:11]
	s_mov_b64 s[2:3], 0x4200
	v_lshl_add_u64 v[2:3], v[0:1], 0, s[2:3]
	s_movk_i32 s2, 0x4000
	v_add_co_u32_e32 v0, vcc, s2, v0
	s_brev_b32 s2, 64
	s_nop 0
	v_addc_co_u32_e32 v1, vcc, 0, v1, vcc
	s_nop 0
	v_rcp_f32_e32 v0, v20
	v_lshlrev_b64 v[20:21], 11, v[210:211]
	s_waitcnt vmcnt(0)
	v_lshlrev_b32_e32 v22, 16, v180
	v_mul_f32_e32 v1, 0xbfb8aa3b, v22
	v_exp_f32_e32 v1, v1
	v_and_b32_e32 v23, 0xffff0000, v180
	v_add_f32_e32 v1, 1.0, v1
	v_rcp_f32_e32 v24, v1
	v_pk_mul_f32 v[26:27], v[108:109], v[0:1] op_sel_hi:[1, 0]
	v_mul_f32_e32 v1, 0xbfb8aa3b, v23
	v_exp_f32_e32 v1, v1
	s_nop 0
	v_add_f32_e32 v1, 1.0, v1
	v_rcp_f32_e32 v25, v1
	s_nop 0
	v_pk_mul_f32 v[22:23], v[24:25], v[22:23]
	v_lshlrev_b32_e32 v24, 16, v181
	v_mul_f32_e32 v1, 0xbfb8aa3b, v24
	v_exp_f32_e32 v1, v1
	v_and_b32_e32 v25, 0xffff0000, v181
	v_pk_mul_f32 v[22:23], v[26:27], v[22:23]
	v_add_f32_e32 v1, 1.0, v1
	v_rcp_f32_e32 v16, v1
	v_pk_mul_f32 v[26:27], v[110:111], v[0:1] op_sel_hi:[1, 0]
	v_mul_f32_e32 v1, 0xbfb8aa3b, v25
	v_exp_f32_e32 v1, v1
	v_cvt_pk_bf16_f32 v22, v22, v23
	v_add_f32_e32 v1, 1.0, v1
	v_rcp_f32_e32 v17, v1
	s_nop 0
	v_pk_mul_f32 v[16:17], v[16:17], v[24:25]
	s_nop 0
	v_pk_mul_f32 v[16:17], v[26:27], v[16:17]
	s_nop 0
	v_cvt_pk_bf16_f32 v23, v16, v17
	v_lshl_add_u64 v[16:17], s[18:19], 0, v[20:21]
	v_lshl_add_u64 v[16:17], v[16:17], 0, s[98:99]
	v_lshl_add_u64 v[16:17], v[16:17], 0, v[10:11]
	global_store_dwordx2 v[16:17], v[22:23], off
	s_waitcnt vmcnt(7)
	v_lshlrev_b32_e32 v16, 16, v182
	v_mul_f32_e32 v1, 0xbfb8aa3b, v16
	v_exp_f32_e32 v1, v1
	v_and_b32_e32 v17, 0xffff0000, v182
	v_add_f32_e32 v1, 1.0, v1
	v_rcp_f32_e32 v22, v1
	v_pk_mul_f32 v[24:25], v[104:105], v[0:1] op_sel_hi:[1, 0]
	v_mul_f32_e32 v1, 0xbfb8aa3b, v17
	v_exp_f32_e32 v1, v1
	s_nop 0
	v_add_f32_e32 v1, 1.0, v1
	v_rcp_f32_e32 v23, v1
	s_nop 0
	v_pk_mul_f32 v[16:17], v[22:23], v[16:17]
	v_lshlrev_b32_e32 v22, 16, v183
	v_mul_f32_e32 v1, 0xbfb8aa3b, v22
	v_exp_f32_e32 v1, v1
	v_and_b32_e32 v23, 0xffff0000, v183
	v_pk_mul_f32 v[16:17], v[24:25], v[16:17]
	v_add_f32_e32 v1, 1.0, v1
	v_rcp_f32_e32 v18, v1
	v_pk_mul_f32 v[24:25], v[106:107], v[0:1] op_sel_hi:[1, 0]
	v_mul_f32_e32 v1, 0xbfb8aa3b, v23
	v_exp_f32_e32 v1, v1
	v_cvt_pk_bf16_f32 v16, v16, v17
	v_add_f32_e32 v1, 1.0, v1
	v_rcp_f32_e32 v19, v1
	s_nop 0
	v_pk_mul_f32 v[18:19], v[18:19], v[22:23]
	s_nop 0
	v_pk_mul_f32 v[18:19], v[24:25], v[18:19]
	s_nop 0
	v_cvt_pk_bf16_f32 v17, v18, v19
	v_lshl_add_u64 v[18:19], s[14:15], 0, v[20:21]
	v_lshl_add_u64 v[18:19], v[18:19], 0, s[98:99]
	v_lshl_add_u64 v[10:11], v[18:19], 0, v[10:11]
	v_add_co_u32_e32 v10, vcc, s2, v10
	s_nop 1
	v_addc_co_u32_e32 v11, vcc, 0, v11, vcc
	global_store_dwordx2 v[10:11], v[16:17], off offset:32
	s_waitcnt vmcnt(7)
	v_lshlrev_b32_e32 v16, 16, v184
	v_mul_f32_e32 v1, 0xbfb8aa3b, v16
	v_exp_f32_e32 v1, v1
	v_and_b32_e32 v17, 0xffff0000, v184
	v_add_f32_e32 v1, 1.0, v1
	v_rcp_f32_e32 v18, v1
	v_pk_mul_f32 v[20:21], v[100:101], v[0:1] op_sel_hi:[1, 0]
	v_mul_f32_e32 v1, 0xbfb8aa3b, v17
	v_exp_f32_e32 v1, v1
	s_nop 0
	v_add_f32_e32 v1, 1.0, v1
	v_rcp_f32_e32 v19, v1
	s_nop 0
	v_pk_mul_f32 v[16:17], v[18:19], v[16:17]
	v_lshlrev_b32_e32 v18, 16, v185
	v_mul_f32_e32 v1, 0xbfb8aa3b, v18
	v_exp_f32_e32 v1, v1
	v_and_b32_e32 v19, 0xffff0000, v185
	v_pk_mul_f32 v[16:17], v[20:21], v[16:17]
	v_add_f32_e32 v1, 1.0, v1
	v_rcp_f32_e32 v14, v1
	v_pk_mul_f32 v[20:21], v[102:103], v[0:1] op_sel_hi:[1, 0]
	v_mul_f32_e32 v1, 0xbfb8aa3b, v19
	v_exp_f32_e32 v1, v1
	v_cvt_pk_bf16_f32 v16, v16, v17
	v_add_f32_e32 v1, 1.0, v1
	v_rcp_f32_e32 v15, v1
	s_nop 0
	v_pk_mul_f32 v[14:15], v[14:15], v[18:19]
	s_nop 0
	v_pk_mul_f32 v[14:15], v[20:21], v[14:15]
	s_nop 0
	v_cvt_pk_bf16_f32 v17, v14, v15
	s_waitcnt vmcnt(6)
	v_lshlrev_b32_e32 v14, 16, v186
	v_mul_f32_e32 v1, 0xbfb8aa3b, v14
	v_exp_f32_e32 v1, v1
	v_and_b32_e32 v15, 0xffff0000, v186
	global_store_dwordx2 v[10:11], v[16:17], off offset:64
	v_add_f32_e32 v1, 1.0, v1
	v_rcp_f32_e32 v16, v1
	v_pk_mul_f32 v[18:19], v[96:97], v[0:1] op_sel_hi:[1, 0]
	v_mul_f32_e32 v1, 0xbfb8aa3b, v15
	v_exp_f32_e32 v1, v1
	s_nop 0
	v_add_f32_e32 v1, 1.0, v1
	v_rcp_f32_e32 v17, v1
	s_nop 0
	v_pk_mul_f32 v[14:15], v[16:17], v[14:15]
	v_lshlrev_b32_e32 v16, 16, v187
	v_mul_f32_e32 v1, 0xbfb8aa3b, v16
	v_exp_f32_e32 v1, v1
	v_and_b32_e32 v17, 0xffff0000, v187
	v_pk_mul_f32 v[14:15], v[18:19], v[14:15]
	v_add_f32_e32 v1, 1.0, v1
	v_rcp_f32_e32 v12, v1
	v_pk_mul_f32 v[18:19], v[98:99], v[0:1] op_sel_hi:[1, 0]
	v_mul_f32_e32 v1, 0xbfb8aa3b, v17
	v_exp_f32_e32 v1, v1
	v_cvt_pk_bf16_f32 v14, v14, v15
	v_add_f32_e32 v1, 1.0, v1
	v_rcp_f32_e32 v13, v1
	s_nop 0
	v_pk_mul_f32 v[12:13], v[12:13], v[16:17]
	s_nop 0
	v_pk_mul_f32 v[12:13], v[18:19], v[12:13]
	s_nop 0
	v_cvt_pk_bf16_f32 v15, v12, v13
	s_waitcnt vmcnt(6)
; DEVI float bfs(short h) { return __uint_as_float(((unsigned)(u16)h) << 16); }
; DEVI float silu_f(float x) { return x * __builtin_amdgcn_rcpf(1.f + __expf(-x)); }
; DEVI void moba_item(const Params& p, int l, int item) {
;   const int tid_ = get_tid();
;   const int bh = item & 15, r = item >> 4;
;   const int qt = (r < 16) ? 31 - r : r - 16;
;   const int b = bh >> 3, h = bh & 7, qblk = qt >> 1;
;   const long t0 = (long)b * S_ + qt * 128;
;   const int tid = tid_, w = tid >> 6, lane = tid & 63, fr = lane & 15, fq = lane >> 4;
;   const u16* proj = p.proj;
;   u16* Kb0 = (u16*)smem;                u16* Vb0 = (u16*)(smem + 34816);
;   u16* Kb1 = (u16*)(smem + 71680);      u16* Vb1 = (u16*)(smem + 71680 + 34816);
;   u16* Qs = Kb1;
;   float* km = (float*)(smem + 71680 + 34816);
;   float* gate = (float*)(smem + 71680 + 34816 + 8192);
;   unsigned* selm = (unsigned*)(smem + 71680 + 34816 + 8192 + 8704);
;   const int kkey = tid >> 4, kdg = tid & 15;
;   bf16x8 pk_[4], pv_[4];
;   {
;     const long tb = (long)b * S_ + qblk * 256;
; #pragma unroll
;     ...
; #pragma unroll
;   for (int ct = 0; ct < 8; ++ct) {
;     int dv = ct * 16 + fq * 4;
;     const bf16x4 gt = gtv[ct];
;     *(bf16x4*)(p.ys + (long)2 * T_ * 1024 + qtok * 1024 + h * 128 + dv) =
;         pack4(oacc[ct][0] * inv * silu_f(bfs(gt[0])), oacc[ct][1] * inv * silu_f(bfs(gt[1])),
;               oacc[ct][2] * inv * silu_f(bfs(gt[2])), oacc[ct][3] * inv * silu_f(bfs(gt[3])));
;   }
	v_lshlrev_b32_e32 v12, 16, v188
	v_mul_f32_e32 v1, 0xbfb8aa3b, v12
	v_exp_f32_e32 v1, v1
	v_and_b32_e32 v13, 0xffff0000, v188
	global_store_dwordx2 v[10:11], v[14:15], off offset:96
	v_add_f32_e32 v1, 1.0, v1
	v_rcp_f32_e32 v14, v1
	v_pk_mul_f32 v[16:17], v[92:93], v[0:1] op_sel_hi:[1, 0]
	v_mul_f32_e32 v1, 0xbfb8aa3b, v13
	v_exp_f32_e32 v1, v1
	s_nop 0
	v_add_f32_e32 v1, 1.0, v1
	v_rcp_f32_e32 v15, v1
	s_nop 0
	v_pk_mul_f32 v[12:13], v[14:15], v[12:13]
	v_lshlrev_b32_e32 v14, 16, v189
	v_mul_f32_e32 v1, 0xbfb8aa3b, v14
	v_exp_f32_e32 v1, v1
	v_and_b32_e32 v15, 0xffff0000, v189
	v_pk_mul_f32 v[12:13], v[16:17], v[12:13]
	v_add_f32_e32 v1, 1.0, v1
	v_rcp_f32_e32 v8, v1
	v_pk_mul_f32 v[16:17], v[94:95], v[0:1] op_sel_hi:[1, 0]
	v_mul_f32_e32 v1, 0xbfb8aa3b, v15
	v_exp_f32_e32 v1, v1
	v_cvt_pk_bf16_f32 v12, v12, v13
	v_add_f32_e32 v1, 1.0, v1
	v_rcp_f32_e32 v9, v1
	s_nop 0
	v_pk_mul_f32 v[8:9], v[8:9], v[14:15]
	s_nop 0
	v_pk_mul_f32 v[8:9], v[16:17], v[8:9]
	s_nop 0
	v_cvt_pk_bf16_f32 v13, v8, v9
	s_waitcnt vmcnt(6)
	v_lshlrev_b32_e32 v8, 16, v190
	v_mul_f32_e32 v1, 0xbfb8aa3b, v8
	v_exp_f32_e32 v1, v1
	v_and_b32_e32 v9, 0xffff0000, v190
	global_store_dwordx2 v[10:11], v[12:13], off offset:128
	v_add_f32_e32 v1, 1.0, v1
	v_rcp_f32_e32 v12, v1
	v_pk_mul_f32 v[14:15], v[84:85], v[0:1] op_sel_hi:[1, 0]
	v_mul_f32_e32 v1, 0xbfb8aa3b, v9
	v_exp_f32_e32 v1, v1
	s_nop 0
	v_add_f32_e32 v1, 1.0, v1
	v_rcp_f32_e32 v13, v1
	s_nop 0
	v_pk_mul_f32 v[8:9], v[12:13], v[8:9]
	v_lshlrev_b32_e32 v12, 16, v191
	v_mul_f32_e32 v1, 0xbfb8aa3b, v12
	v_exp_f32_e32 v1, v1
	v_and_b32_e32 v13, 0xffff0000, v191
	v_pk_mul_f32 v[8:9], v[14:15], v[8:9]
	v_add_f32_e32 v1, 1.0, v1
	v_rcp_f32_e32 v6, v1
	v_pk_mul_f32 v[14:15], v[86:87], v[0:1] op_sel_hi:[1, 0]
	v_mul_f32_e32 v1, 0xbfb8aa3b, v13
	v_exp_f32_e32 v1, v1
	v_cvt_pk_bf16_f32 v8, v8, v9
	v_add_f32_e32 v1, 1.0, v1
	v_rcp_f32_e32 v7, v1
	s_nop 0
	v_pk_mul_f32 v[6:7], v[6:7], v[12:13]
	s_nop 0
	v_pk_mul_f32 v[6:7], v[14:15], v[6:7]
	s_nop 0
	v_cvt_pk_bf16_f32 v9, v6, v7
	s_waitcnt vmcnt(6)
	v_lshlrev_b32_e32 v6, 16, v192
	v_mul_f32_e32 v1, 0xbfb8aa3b, v6
	v_exp_f32_e32 v1, v1
	v_and_b32_e32 v7, 0xffff0000, v192
	global_store_dwordx2 v[10:11], v[8:9], off offset:160
	v_add_f32_e32 v1, 1.0, v1
	v_rcp_f32_e32 v8, v1
	v_pk_mul_f32 v[12:13], v[88:89], v[0:1] op_sel_hi:[1, 0]
	v_mul_f32_e32 v1, 0xbfb8aa3b, v7
	v_exp_f32_e32 v1, v1
	s_nop 0
	v_add_f32_e32 v1, 1.0, v1
	v_rcp_f32_e32 v9, v1
	s_nop 0
	v_pk_mul_f32 v[6:7], v[8:9], v[6:7]
	v_lshlrev_b32_e32 v8, 16, v193
	v_mul_f32_e32 v1, 0xbfb8aa3b, v8
	v_exp_f32_e32 v1, v1
	v_and_b32_e32 v9, 0xffff0000, v193
	v_pk_mul_f32 v[6:7], v[12:13], v[6:7]
	v_add_f32_e32 v1, 1.0, v1
	v_rcp_f32_e32 v4, v1
	v_pk_mul_f32 v[12:13], v[90:91], v[0:1] op_sel_hi:[1, 0]
	v_mul_f32_e32 v1, 0xbfb8aa3b, v9
	v_exp_f32_e32 v1, v1
	v_cvt_pk_bf16_f32 v6, v6, v7
	v_add_f32_e32 v1, 1.0, v1
	v_rcp_f32_e32 v5, v1
	s_nop 0
	v_pk_mul_f32 v[4:5], v[4:5], v[8:9]
	s_nop 0
	v_pk_mul_f32 v[4:5], v[12:13], v[4:5]
	s_nop 0
	v_cvt_pk_bf16_f32 v7, v4, v5
	s_waitcnt vmcnt(6)
	v_lshlrev_b32_e32 v4, 16, v194
	v_mul_f32_e32 v1, 0xbfb8aa3b, v4
	v_exp_f32_e32 v1, v1
	v_and_b32_e32 v5, 0xffff0000, v194
	global_store_dwordx2 v[10:11], v[6:7], off offset:192
	v_add_f32_e32 v1, 1.0, v1
	v_rcp_f32_e32 v6, v1
	v_pk_mul_f32 v[8:9], v[80:81], v[0:1] op_sel_hi:[1, 0]
	v_mul_f32_e32 v1, 0xbfb8aa3b, v5
	v_exp_f32_e32 v1, v1
	s_nop 0
	v_add_f32_e32 v1, 1.0, v1
	v_rcp_f32_e32 v7, v1
	s_nop 0
	v_pk_mul_f32 v[4:5], v[6:7], v[4:5]
	v_and_b32_e32 v7, 0xffff0000, v195
	v_lshlrev_b32_e32 v6, 16, v195
	v_mul_f32_e32 v1, 0xbfb8aa3b, v6
	v_mul_f32_e32 v3, 0xbfb8aa3b, v7
	v_exp_f32_e32 v1, v1
	v_exp_f32_e32 v3, v3
	v_pk_mul_f32 v[4:5], v[8:9], v[4:5]
	v_add_f32_e32 v1, 1.0, v1
	v_add_f32_e32 v3, 1.0, v3
	v_rcp_f32_e32 v2, v1
	v_rcp_f32_e32 v3, v3
	v_pk_mul_f32 v[0:1], v[82:83], v[0:1] op_sel_hi:[1,0]
	v_pk_mul_f32 v[2:3], v[2:3], v[6:7]
	s_nop 0
	v_pk_mul_f32 v[0:1], v[0:1], v[2:3]
	v_cvt_pk_bf16_f32 v2, v4, v5
	v_cvt_pk_bf16_f32 v3, v0, v1
	global_store_dwordx2 v[10:11], v[2:3], off offset:224
	s_barrier
	s_load_dword s2, s[52:53], 0x0
	s_waitcnt lgkmcnt(0)
	s_add_i32 s26, s2, s26
	s_cmpk_gt_i32 s26, 0x1ff
	s_cbranch_scc1 .LBB0_671
.LBB0_494:
	s_ashr_i32 s2, s26, 4
	s_sub_i32 s3, 31, s2
	s_add_i32 s6, s2, -16
	s_cmp_lt_i32 s2, 16
	s_cselect_b32 s20, s3, s6
	s_lshr_b32 s28, s20, 1
	s_lshl_b32 s2, s26, 9
	v_mov_b32_e32 v48, v234
	s_and_b32 s29, s2, 0x1000
	s_lshl_b32 s2, s28, 8
	s_add_i32 s2, s2, s29
	v_lshrrev_b32_e32 v154, 4, v48
	v_or_b32_e32 v24, s2, v154
	s_lshl_b32 s2, s26, 7
	s_and_b32 s6, s2, 0x380
	v_mov_b64_e32 v[36:37], s[92:93]
	v_and_b32_e32 v50, 15, v48
	v_mad_u64_u32 v[0:1], s[2:3], v24, s97, v[36:37]
	s_lshl_b32 s98, s6, 1
	v_lshlrev_b32_e32 v210, 4, v50
	v_lshl_add_u64 v[0:1], v[0:1], 0, s[98:99]
	v_or_b32_e32 v8, 32, v24
	v_lshl_add_u64 v[0:1], v[0:1], 0, v[210:211]
	v_mad_u64_u32 v[8:9], s[2:3], v8, s97, v[36:37]
	v_add_co_u32_e32 v4, vcc, s68, v0
	v_lshl_add_u64 v[8:9], v[8:9], 0, s[98:99]
	v_or_b32_e32 v16, 64, v24
	v_addc_co_u32_e32 v5, vcc, 0, v1, vcc
	v_lshl_add_u64 v[8:9], v[8:9], 0, v[210:211]
	v_mad_u64_u32 v[16:17], s[2:3], v16, s97, v[36:37]
	s_lshl_b32 s27, s20, 7
	v_add_co_u32_e32 v12, vcc, s68, v8
	v_lshl_add_u64 v[16:17], v[16:17], 0, s[98:99]
	v_or_b32_e32 v24, 0x60, v24
	s_add_i32 s27, s27, s29
	v_addc_co_u32_e32 v13, vcc, 0, v9, vcc
	v_lshl_add_u64 v[16:17], v[16:17], 0, v[210:211]
	v_mad_u64_u32 v[24:25], s[2:3], v24, s97, v[36:37]
	v_add_co_u32_e32 v20, vcc, s68, v16
	v_lshl_add_u64 v[24:25], v[24:25], 0, s[98:99]
	v_lshlrev_b32_e32 v32, 4, v48
	v_or_b32_e32 v38, s27, v154
	v_addc_co_u32_e32 v21, vcc, 0, v17, vcc
; DEVI void moba_item(const Params& p, int l, int item) {
;     ...
;   {
;     const long tb = (long)b * S_ + qblk * 256;
; #pragma unroll
;     for (int i = 0; i < 4; ++i) {
;       pk_[i] = *(const bf16x8*)(proj + (tb + kkey + 32 * i) * NP + C_CK + h * 128 + kdg * 8);
;       pv_[i] = *(const bf16x8*)(proj + (tb + kkey + 32 * i) * NP + C_CV + h * 128 + kdg * 8);
;     }
;   }
; #pragma unroll
;   for (int i = 0; i < 4; ++i) {
;     int ch = tid + i * 512;
;     int row = ch >> 4, dg = ch & 15;
;     *(bf16x8*)(Qs + row * 136 + dg * 8) = *(const bf16x8*)(proj + (t0 + row) * NP + C_CQ + h * 128 + dg * 8);
;   }
;   for (int i = tid; i < qblk * 128; i += 512) km[i] = p.kmean[(long)(bh * 16) * 128 + i];
;   if (tid == 0) selm[128] = 0u;
;   __syncthreads();
	v_lshl_add_u64 v[24:25], v[24:25], 0, v[210:211]
	v_and_b32_e32 v210, 0xf0, v32
	v_mad_u64_u32 v[32:33], s[2:3], v38, s97, v[36:37]
	v_add_co_u32_e32 v28, vcc, s68, v24
	v_lshl_add_u64 v[32:33], v[32:33], 0, s[98:99]
	s_nop 0
	v_addc_co_u32_e32 v29, vcc, 0, v25, vcc
	v_lshl_add_u64 v[32:33], v[32:33], 0, v[210:211]
	v_add_co_u32_e32 v32, vcc, s57, v32
	s_nop 1
	v_addc_co_u32_e32 v33, vcc, 0, v33, vcc
	v_mul_u32_u24_e32 v155, 0x110, v154
	global_load_dwordx4 v[180:183], v[32:33], off offset:2560
	v_add3_u32 v196, s70, v210, v155
	s_lshl_b32 s10, s28, 7
	v_or_b32_e32 v32, 32, v38
	v_mad_u64_u32 v[32:33], s[2:3], v32, s97, v[36:37]
	v_lshl_add_u64 v[32:33], v[32:33], 0, s[98:99]
	v_lshl_add_u64 v[32:33], v[32:33], 0, v[210:211]
	v_add_co_u32_e32 v32, vcc, s57, v32
	s_nop 1
	v_addc_co_u32_e32 v33, vcc, 0, v33, vcc
	global_load_dwordx4 v[184:187], v[32:33], off offset:2560
	v_or_b32_e32 v32, 64, v38
	v_mad_u64_u32 v[32:33], s[2:3], v32, s97, v[36:37]
	v_lshl_add_u64 v[32:33], v[32:33], 0, s[98:99]
	v_lshl_add_u64 v[32:33], v[32:33], 0, v[210:211]
	v_add_co_u32_e32 v32, vcc, s57, v32
	s_nop 1
	v_addc_co_u32_e32 v33, vcc, 0, v33, vcc
	global_load_dwordx4 v[188:191], v[32:33], off offset:2560
	v_or_b32_e32 v32, 0x60, v38
	v_mad_u64_u32 v[32:33], s[2:3], v32, s97, v[36:37]
	v_lshl_add_u64 v[32:33], v[32:33], 0, s[98:99]
	v_lshl_add_u64 v[32:33], v[32:33], 0, v[210:211]
	v_add_co_u32_e32 v32, vcc, 0x2000, v32
	s_nop 1
	v_addc_co_u32_e32 v33, vcc, 0, v33, vcc
	global_load_dwordx4 v[192:195], v[32:33], off offset:2560
	s_and_b32 s11, s26, 15
	s_lshl_b32 s21, s11, 11
	v_add_u32_e32 v210, s21, v48
	v_lshrrev_b32_e32 v44, 7, v48
	v_and_b32_e32 v45, 0x7f, v48
	v_mul_u32_u24_e32 v44, 0x210, v44
	v_lshl_add_u32 v45, v45, 2, v44
	v_add_u32_e32 v36, 0x1e800, v45
	v_lshl_add_u64 v[40:41], v[210:211], 2, s[44:45]
	v_add_u32_e32 v37, 0x200, v48
	v_add_u32_e32 v38, 0x400, v48
	v_add_co_u32_e32 v42, vcc, 0x1000, v40
	v_add_u32_e32 v39, 0x600, v48
	s_nop 1
	v_addc_co_u32_e32 v43, vcc, 0, v41, vcc
	v_cmp_gt_u32_e32 vcc, s10, v48
	s_and_saveexec_b64 s[6:7], vcc
	global_load_dword v197, v[40:41], off
	s_mov_b64 exec, s[6:7]
	v_cmp_gt_u32_e32 vcc, s10, v37
	s_and_saveexec_b64 s[6:7], vcc
	global_load_dword v198, v[40:41], off offset:2048
	s_mov_b64 exec, s[6:7]
	v_cmp_gt_u32_e32 vcc, s10, v38
	s_and_saveexec_b64 s[6:7], vcc
	global_load_dword v199, v[42:43], off
	s_mov_b64 exec, s[6:7]
	v_cmp_gt_u32_e32 vcc, s10, v39
	s_and_saveexec_b64 s[6:7], vcc
	global_load_dword v200, v[42:43], off offset:2048
	s_mov_b64 exec, s[6:7]
	global_load_dwordx4 v[0:3], v[4:5], off offset:512
	s_nop 0
	global_load_dwordx4 v[4:7], v[4:5], off offset:2560
	s_nop 0
	global_load_dwordx4 v[8:11], v[12:13], off offset:512
	s_nop 0
	global_load_dwordx4 v[12:15], v[12:13], off offset:2560
	s_nop 0
	global_load_dwordx4 v[16:19], v[20:21], off offset:512
	s_nop 0
	global_load_dwordx4 v[20:23], v[20:21], off offset:2560
	s_nop 0
	global_load_dwordx4 v[24:27], v[28:29], off offset:512
	s_nop 0
	global_load_dwordx4 v[28:31], v[28:29], off offset:2560
	s_nop 0
	s_waitcnt vmcnt(8)
	ds_write_b128 v196, v[180:183]
	ds_write_b128 v196, v[184:187] offset:8704
	ds_write_b128 v196, v[188:191] offset:17408
	ds_write_b128 v196, v[192:195] offset:26112
	v_cmp_gt_u32_e32 vcc, s10, v48
	s_and_saveexec_b64 s[6:7], vcc
	ds_write_b32 v36, v197
	s_mov_b64 exec, s[6:7]
	v_cmp_gt_u32_e32 vcc, s10, v37
	s_and_saveexec_b64 s[6:7], vcc
	ds_write_b32 v36, v198 offset:2112
	s_mov_b64 exec, s[6:7]
	v_cmp_gt_u32_e32 vcc, s10, v38
	s_and_saveexec_b64 s[6:7], vcc
	ds_write_b32 v36, v199 offset:4224
	s_mov_b64 exec, s[6:7]
	v_cmp_gt_u32_e32 vcc, s10, v39
	s_and_saveexec_b64 s[6:7], vcc
	ds_write_b32 v36, v200 offset:6336
	s_mov_b64 exec, s[6:7]
	v_cmp_eq_u32_e32 vcc, 0, v48
	s_and_saveexec_b64 s[2:3], vcc
	v_mov_b32_e32 v32, s73
	ds_write_b32 v32, v211
	s_or_b64 exec, exec, s[2:3]
	v_and_b32_e32 v40, 0x7f, v48
	v_mad_u32_u24 v32, v40, s71, 0
	v_add_u32_e32 v32, 0x11800, v32
	s_waitcnt lgkmcnt(0)
	s_barrier
	s_cmp_eq_u32 s28, 0
	s_cbranch_scc1 .Lmy_gd_done
; DEVI float bfs(short h) { return __uint_as_float(((unsigned)(u16)h) << 16); }
; DEVI void moba_item(const Params& p, int l, int item) {
;     ...
;   {
;     const int q = tid & 127, part = tid >> 7;
;     float dots[4] = {0.f, 0.f, 0.f, 0.f};
; #pragma unroll
;     for (int c = 0; c < 16; ++c) {
;       const bf16x8 qv = *(const bf16x8*)(Qs + q * 136 + c * 8);
;       float qf[8];
; #pragma unroll
;       for (int e = 0; e < 8; ++e) qf[e] = bfs(qv[e]);
; #pragma unroll
;       for (int k = 0; k < 4; ++k) {
;         const int blk = part + 4 * k;
;         if (blk < qblk) {
; #pragma unroll
;           for (int e = 0; e < 8; ++e) dots[k] += qf[e] * km[blk * 128 + c * 8 + e];
;         }
;       }
;     }
; #pragma unroll
;     for (int k = 0; k < 4; ++k) {
;       const int blk = part + 4 * k;
;       if (blk < qblk) gate[q * 17 + blk] = dots[k];
;     }
;   }
	v_and_b32_e32 v35, 63, v48
	v_lshrrev_b32_e32 v36, 6, v48
	v_and_b32_e32 v37, 15, v35
	v_lshrrev_b32_e32 v38, 4, v35
	v_lshl_add_u32 v39, v36, 4, v37
	v_mul_u32_u24_e32 v32, 0x110, v39
	v_mul_u32_u24_e32 v33, 0x210, v37
	v_mov_b32_e32 v34, s96
	v_lshl_add_u32 v32, v38, 6, v32
	v_lshl_add_u32 v33, v38, 7, v33
	v_mad_u32_u24 v34, v39, s74, v34
	v_add_u32_e32 v32, 0x11800, v32
	v_add_u32_e32 v33, 0x1e800, v33
	v_lshl_add_u32 v34, v38, 4, v34
	ds_read_b128 v[56:59], v32
	ds_read_b128 v[72:75], v33
	ds_read_b128 v[76:79], v33 offset:16
	ds_read_b128 v[60:63], v32 offset:16
	ds_read_b128 v[80:83], v33 offset:32
	ds_read_b128 v[84:87], v33 offset:48
	ds_read_b128 v[64:67], v32 offset:32
	ds_read_b128 v[88:91], v33 offset:64
	ds_read_b128 v[92:95], v33 offset:80
	ds_read_b128 v[68:71], v32 offset:48
	ds_read_b128 v[96:99], v33 offset:96
	ds_read_b128 v[100:103], v33 offset:112
	v_mov_b32_e32 v136, 0
	v_mov_b32_e32 v137, 0
	v_mov_b32_e32 v138, 0
	v_mov_b32_e32 v139, 0
	s_waitcnt lgkmcnt(9)
	v_lshlrev_b32_e32 v104, 16, v56
	v_and_b32_e32 v105, 0xffff0000, v56
	v_lshlrev_b32_e32 v106, 16, v57
	v_and_b32_e32 v107, 0xffff0000, v57
	v_lshlrev_b32_e32 v108, 16, v58
	v_and_b32_e32 v109, 0xffff0000, v58
	v_lshlrev_b32_e32 v110, 16, v59
	v_and_b32_e32 v111, 0xffff0000, v59
	v_mfma_f32_16x16x4_f32 v[136:139], v72, v104, v[136:139]
	v_mfma_f32_16x16x4_f32 v[136:139], v73, v105, v[136:139]
	v_mfma_f32_16x16x4_f32 v[136:139], v74, v106, v[136:139]
	v_mfma_f32_16x16x4_f32 v[136:139], v75, v107, v[136:139]
	v_mfma_f32_16x16x4_f32 v[136:139], v76, v108, v[136:139]
	v_mfma_f32_16x16x4_f32 v[136:139], v77, v109, v[136:139]
	v_mfma_f32_16x16x4_f32 v[136:139], v78, v110, v[136:139]
	v_mfma_f32_16x16x4_f32 v[136:139], v79, v111, v[136:139]
	s_waitcnt lgkmcnt(6)
	v_lshlrev_b32_e32 v112, 16, v60
	v_and_b32_e32 v113, 0xffff0000, v60
	v_lshlrev_b32_e32 v114, 16, v61
	v_and_b32_e32 v115, 0xffff0000, v61
	v_lshlrev_b32_e32 v116, 16, v62
	v_and_b32_e32 v117, 0xffff0000, v62
	v_lshlrev_b32_e32 v118, 16, v63
	v_and_b32_e32 v119, 0xffff0000, v63
	v_mfma_f32_16x16x4_f32 v[136:139], v80, v112, v[136:139]
	v_mfma_f32_16x16x4_f32 v[136:139], v81, v113, v[136:139]
	v_mfma_f32_16x16x4_f32 v[136:139], v82, v114, v[136:139]
	v_mfma_f32_16x16x4_f32 v[136:139], v83, v115, v[136:139]
	v_mfma_f32_16x16x4_f32 v[136:139], v84, v116, v[136:139]
	v_mfma_f32_16x16x4_f32 v[136:139], v85, v117, v[136:139]
	v_mfma_f32_16x16x4_f32 v[136:139], v86, v118, v[136:139]
	v_mfma_f32_16x16x4_f32 v[136:139], v87, v119, v[136:139]
	s_waitcnt lgkmcnt(3)
	v_lshlrev_b32_e32 v120, 16, v64
	v_and_b32_e32 v121, 0xffff0000, v64
	v_lshlrev_b32_e32 v122, 16, v65
	v_and_b32_e32 v123, 0xffff0000, v65
	v_lshlrev_b32_e32 v124, 16, v66
	v_and_b32_e32 v125, 0xffff0000, v66
	v_lshlrev_b32_e32 v126, 16, v67
	v_and_b32_e32 v127, 0xffff0000, v67
	v_mfma_f32_16x16x4_f32 v[136:139], v88, v120, v[136:139]
	v_mfma_f32_16x16x4_f32 v[136:139], v89, v121, v[136:139]
	v_mfma_f32_16x16x4_f32 v[136:139], v90, v122, v[136:139]
	v_mfma_f32_16x16x4_f32 v[136:139], v91, v123, v[136:139]
	v_mfma_f32_16x16x4_f32 v[136:139], v92, v124, v[136:139]
	v_mfma_f32_16x16x4_f32 v[136:139], v93, v125, v[136:139]
	v_mfma_f32_16x16x4_f32 v[136:139], v94, v126, v[136:139]
	v_mfma_f32_16x16x4_f32 v[136:139], v95, v127, v[136:139]
	s_waitcnt lgkmcnt(0)
	v_lshlrev_b32_e32 v128, 16, v68
	v_and_b32_e32 v129, 0xffff0000, v68
	v_lshlrev_b32_e32 v130, 16, v69
	v_and_b32_e32 v131, 0xffff0000, v69
	v_lshlrev_b32_e32 v132, 16, v70
	v_and_b32_e32 v133, 0xffff0000, v70
	v_lshlrev_b32_e32 v134, 16, v71
	v_and_b32_e32 v135, 0xffff0000, v71
	v_mfma_f32_16x16x4_f32 v[136:139], v96, v128, v[136:139]
	v_mfma_f32_16x16x4_f32 v[136:139], v97, v129, v[136:139]
	v_mfma_f32_16x16x4_f32 v[136:139], v98, v130, v[136:139]
	v_mfma_f32_16x16x4_f32 v[136:139], v99, v131, v[136:139]
	v_mfma_f32_16x16x4_f32 v[136:139], v100, v132, v[136:139]
	v_mfma_f32_16x16x4_f32 v[136:139], v101, v133, v[136:139]
	v_mfma_f32_16x16x4_f32 v[136:139], v102, v134, v[136:139]
	v_mfma_f32_16x16x4_f32 v[136:139], v103, v135, v[136:139]
	s_nop 9
	ds_write2_b32 v34, v136, v137 offset1:1
	ds_write2_b32 v34, v138, v139 offset0:2 offset1:3

; DEVI void moba_item(const Params& p, int l, int item) {
;     ...
;   bf16x8 qb[4];
; #pragma unroll
;   for (int ks = 0; ks < 4; ++ks) qb[ks] = *(const bf16x8*)(Qs + (w * 16 + fr) * 136 + ks * 32 + fq * 8);
; #pragma unroll
;   for (int i = 0; i < 4; ++i) {
;     *(bf16x8*)(Kb0 + (kkey + 32 * i) * 136 + kdg * 8) = pk_[i];
;     *(bf16x8*)(Vb0 + (kkey + 32 * i) * 144 + kdg * 8) = pv_[i];
;   }
;   __syncthreads();
;   unsigned pend = selm[128];
;   const unsigned mysel = selm[w * 16 + fr];
;   __syncthreads();
;   float m = -INFINITY, lsum = 0.f;
;   f32x4 oacc[8];
; #pragma unroll
;   for (int ct = 0; ct < 8; ++ct) oacc[ct] = f32x4{0.f, 0.f, 0.f, 0.f};
;   const int qinb = (qt & 1) * 128 + w * 16 + fr;
;   int cblk = qblk, chalf = 0;
;   int nblk, nhalf;
;     ...
;   MOBA_NEXT(cblk, chalf, nblk, nhalf);
;   if (nblk >= 0) MOBA_LOAD(nblk, nhalf);
;     ...
;   for (int ct = 0; ct < 8; ++ct) gtv[ct] = *(const bf16x4*)(proj + qtok * NP + C_CGATE + h * 128 + ct * 16 + fq * 4);
.LBB0_653:
	s_or_b64 exec, exec, s[2:3]
	s_waitcnt vmcnt(0)
	v_lshrrev_b32_e32 v32, 2, v48
	v_and_b32_e32 v51, 0x70, v32
	v_lshlrev_b32_e32 v52, 3, v50
	v_and_b32_e32 v49, 3, v154
	v_or_b32_e32 v156, v51, v50
	v_mul_u32_u24_e32 v32, 0x110, v156
	v_lshlrev_b32_e32 v33, 4, v49
	v_lshl_add_u32 v53, v52, 1, 0
	v_add3_u32 v44, s70, v32, v33
	v_add_u32_e32 v54, v53, v155
	v_mad_u32_u24 v53, v154, s75, v53
	v_or_b32_e32 v200, s27, v156
	v_mov_b64_e32 v[196:197], s[92:93]
	v_lshlrev_b32_e32 v198, 3, v49
	v_mad_u64_u32 v[196:197], s[10:11], v200, s97, v[196:197]
	v_lshl_add_u64 v[196:197], v[196:197], 0, s[98:99]
	v_add_co_u32_e32 v196, vcc, v198, v196
	s_nop 1
	v_addc_co_u32_e32 v197, vcc, 0, v197, vcc
	v_add_co_u32_e32 v196, vcc, 0x4200, v196
	s_nop 1
	v_addc_co_u32_e32 v197, vcc, 0, v197, vcc
	global_load_dwordx2 v[180:181], v[196:197], off
	global_load_dwordx2 v[182:183], v[196:197], off offset:32
	global_load_dwordx2 v[184:185], v[196:197], off offset:64
	global_load_dwordx2 v[186:187], v[196:197], off offset:96
	global_load_dwordx2 v[188:189], v[196:197], off offset:128
	global_load_dwordx2 v[190:191], v[196:197], off offset:160
	global_load_dwordx2 v[192:193], v[196:197], off offset:192
	global_load_dwordx2 v[194:195], v[196:197], off offset:224
	ds_read_b128 v[32:35], v44
	ds_read_b128 v[36:39], v44 offset:64
	ds_read_b128 v[40:43], v44 offset:128
	ds_read_b128 v[44:47], v44 offset:192
	ds_write_b128 v54, v[0:3]
	ds_write_b128 v53, v[4:7] offset:34816
	ds_write_b128 v54, v[8:11] offset:8704
	ds_write_b128 v53, v[12:15] offset:44032
	ds_write_b128 v54, v[16:19] offset:17408
	ds_write_b128 v53, v[20:23] offset:53248
	ds_write_b128 v54, v[24:27] offset:26112
	ds_write_b128 v53, v[28:31] offset:62464
	v_mov_b32_e32 v53, s73
	s_waitcnt lgkmcnt(0)
	s_barrier
	ds_read_b32 v53, v53
	s_and_b32 s8, s20, 1
	v_lshl_add_u32 v54, v156, 2, 0
	s_lshl_b32 s3, s8, 7
	v_add_u32_e32 v54, 0x1e200, v54
	s_waitcnt lgkmcnt(0)
	v_readfirstlane_b32 s2, v53
	v_subrev_co_u32_e32 v53, vcc, 1, v53
	s_ff1_i32_b32 s9, s2
	s_and_b64 s[6:7], vcc, exec
	ds_read_b32 v157, v54
	s_cselect_b32 s7, -1, s9
	s_cmp_eq_u32 s8, 0
	s_cselect_b64 s[8:9], -1, 0
	s_and_b64 s[10:11], s[8:9], exec
	s_cselect_b32 s34, s7, s28
	v_readfirstlane_b32 s6, v53
	s_cmp_lt_i32 s34, 0
	v_lshlrev_b32_e32 v210, 1, v52
	s_waitcnt lgkmcnt(0)
	s_barrier
	s_cbranch_scc1 .LBB0_655
	s_lshl_b32 s7, s34, 8
	s_add_i32 s7, s7, s29
	s_or_b32 s7, s7, s3
	v_or_b32_e32 v26, s7, v154
	v_mov_b64_e32 v[24:25], s[92:93]
	v_mad_u64_u32 v[0:1], s[10:11], v26, s97, v[24:25]
	v_lshl_add_u64 v[0:1], v[0:1], 0, s[98:99]
	v_or_b32_e32 v8, 32, v26
	v_lshl_add_u64 v[0:1], v[0:1], 0, v[210:211]
	v_mad_u64_u32 v[8:9], s[10:11], v8, s97, v[24:25]
	v_add_co_u32_e32 v4, vcc, 0x3000, v0
	v_lshl_add_u64 v[8:9], v[8:9], 0, s[98:99]
	v_or_b32_e32 v16, 64, v26
	v_addc_co_u32_e32 v5, vcc, 0, v1, vcc
	v_lshl_add_u64 v[8:9], v[8:9], 0, v[210:211]
	v_mad_u64_u32 v[16:17], s[10:11], v16, s97, v[24:25]
	v_add_co_u32_e32 v12, vcc, 0x3000, v8
	v_lshl_add_u64 v[16:17], v[16:17], 0, s[98:99]
	v_or_b32_e32 v26, 0x60, v26
	v_addc_co_u32_e32 v13, vcc, 0, v9, vcc
	v_lshl_add_u64 v[16:17], v[16:17], 0, v[210:211]
	v_mad_u64_u32 v[24:25], s[10:11], v26, s97, v[24:25]
	v_add_co_u32_e32 v20, vcc, 0x3000, v16
	v_lshl_add_u64 v[24:25], v[24:25], 0, s[98:99]
	s_nop 0
	v_addc_co_u32_e32 v21, vcc, 0, v17, vcc
	v_lshl_add_u64 v[24:25], v[24:25], 0, v[210:211]
	v_add_co_u32_e32 v28, vcc, 0x3000, v24
	global_load_dwordx4 v[0:3], v[4:5], off offset:512
	s_nop 0
	global_load_dwordx4 v[4:7], v[4:5], off offset:2560
	v_addc_co_u32_e32 v29, vcc, 0, v25, vcc
	global_load_dwordx4 v[8:11], v[12:13], off offset:512
	s_nop 0
	global_load_dwordx4 v[12:15], v[12:13], off offset:2560
	s_nop 0
	global_load_dwordx4 v[16:19], v[20:21], off offset:512
	s_nop 0
	global_load_dwordx4 v[20:23], v[20:21], off offset:2560
	s_nop 0
	global_load_dwordx4 v[24:27], v[28:29], off offset:512
	s_nop 0
	global_load_dwordx4 v[28:31], v[28:29], off offset:2560
